# code placement: loop heads 64-byte aligned and every MFMA run padded (in the load segment) to start 8-byte aligned
# baseline (speedup 1.0000x reference)
; #define LAS __attribute__((address_space(3)))
; #define BAR() { __builtin_amdgcn_sched_barrier(0); __builtin_amdgcn_s_barrier(); asm volatile("" ::: "memory"); __builtin_amdgcn_sched_barrier(0); }
; DI void gemm_stream2(const bf16_t* __restrict__ A, int lda, const bf16_t* __restrict__ Bt, int ldb, int K, int m0, int n0, ...
;     ...
;     for (int kt = 0; kt < nk; ++kt) {
;         const bool pf = (kt + 2 < nk) || has_next, more = (kt + 1 < nk) || has_next;
;         const bf16_t* pa = (kt + 2 < nk) ? ga + (kt + 2) * 64 : gan + (kt + 2 - nk) * 64;
;         const bf16_t* pb = (kt + 2 < nk) ? gb + (kt + 2) * 64 : gbn + (kt + 2 - nk) * 64;
;         const int plda = (kt + 2 < nk) ? lda : ldan, pldb = (kt + 2 < nk) ? ldb : ldbn;
;         const int s2 = st >= 1 ? st - 1 : 2;
;         const LAS char* base = lds + st * 49152;
; #pragma unroll
;         for (int ks = 0; ks < 2; ++ks) {
;             const unsigned fo = ks ? fo1 : fo0;
;             bf16x8 af[4], bfr[4];
; #pragma unroll
;             for (int i = 0; i < 4; ++i) { af[i] = *(const LAS bf16x8*)(base + aoff + i * 2048 + fo); bfr[i] = *(const LAS bf16x8*)(base + boff + i * 2048 + fo); }
;             if (ks == 1 && more) { if (pf) asm volatile("s_waitcnt vmcnt(3)" ::: "memory"); else asm volatile("s_waitcnt vmcnt(0)" ::: "memory"); }
;             if (pf) { PIECE(s2, ks * 3 + 0); PIECE(s2, ks * 3 + 1); PIECE(s2, ks * 3 + 2); }
;             asm volatile("s_waitcnt lgkmcnt(0)" ::: "memory");
;             BAR();
;             __builtin_amdgcn_s_setprio(1);
; #pragma unroll
;             for (int mi = 0; mi < 4; ++mi)
; #pragma unroll
;                 for (int ni = 0; ni < 4; ++ni) acc[mi][ni] = __builtin_amdgcn_mfma_f32_16x16x32_bf16(bfr[ni], af[mi], acc[mi][ni], 0, 0, 0);
;             __builtin_amdgcn_s_setprio(0);
;             BAR();
;         }
.Lgu_kloop:
	ds_read_b128 v[0:3], v188 offset:16
	ds_read_b128 v[4:7], v189 offset:16
	ds_read_b128 v[8:11], v188 offset:2064
	ds_read_b128 v[12:15], v189 offset:2064
	ds_read_b128 v[196:199], v188 offset:16400
	ds_read_b128 v[200:203], v189 offset:16400
	ds_read_b128 v[204:207], v188 offset:18448
	ds_read_b128 v[208:211], v189 offset:18448
	ds_read_b128 v[152:155], v186 offset:16
	ds_read_b128 v[156:159], v187 offset:16
	ds_read_b128 v[160:163], v186 offset:2064
	ds_read_b128 v[164:167], v187 offset:2064
	ds_read_b128 v[168:171], v186 offset:4112
	ds_read_b128 v[172:175], v187 offset:4112
	ds_read_b128 v[176:179], v186 offset:6160
	ds_read_b128 v[180:183], v187 offset:6160
	s_add_i32 m0, s39, 0xc000
	s_nop 0
	global_load_lds_dwordx4 v184, s[68:69]
	s_add_i32 m0, s39, 0xc400
	s_nop 0
	global_load_lds_dwordx4 v185, s[68:69]
	s_add_u32 s68, s68, 0x80
	s_addc_u32 s69, s69, 0
	s_waitcnt lgkmcnt(0)
	s_waitcnt vmcnt(8)
	s_nop 0
	s_barrier
	s_setprio 1
	v_mfma_f32_16x16x32_bf16 v[24:27], v[0:3], v[152:155], v[24:27]
	v_mfma_f32_16x16x32_bf16 v[28:31], v[8:11], v[152:155], v[28:31]
	v_mfma_f32_16x16x32_bf16 v[32:35], v[0:3], v[160:163], v[32:35]
	v_mfma_f32_16x16x32_bf16 v[36:39], v[8:11], v[160:163], v[36:39]
	v_mfma_f32_16x16x32_bf16 v[40:43], v[0:3], v[168:171], v[40:43]
	v_mfma_f32_16x16x32_bf16 v[44:47], v[8:11], v[168:171], v[44:47]
	v_mfma_f32_16x16x32_bf16 v[48:51], v[0:3], v[176:179], v[48:51]
	v_mfma_f32_16x16x32_bf16 v[52:55], v[8:11], v[176:179], v[52:55]
	v_mfma_f32_16x16x32_bf16 v[24:27], v[4:7], v[156:159], v[24:27]
	v_mfma_f32_16x16x32_bf16 v[28:31], v[12:15], v[156:159], v[28:31]
	v_mfma_f32_16x16x32_bf16 v[32:35], v[4:7], v[164:167], v[32:35]
	v_mfma_f32_16x16x32_bf16 v[36:39], v[12:15], v[164:167], v[36:39]
	v_mfma_f32_16x16x32_bf16 v[40:43], v[4:7], v[172:175], v[40:43]
	v_mfma_f32_16x16x32_bf16 v[44:47], v[12:15], v[172:175], v[44:47]
	v_mfma_f32_16x16x32_bf16 v[48:51], v[4:7], v[180:183], v[48:51]
	v_mfma_f32_16x16x32_bf16 v[52:55], v[12:15], v[180:183], v[52:55]
	v_mfma_f32_16x16x32_bf16 v[56:59], v[196:199], v[152:155], v[56:59]
	v_mfma_f32_16x16x32_bf16 v[60:63], v[204:207], v[152:155], v[60:63]
	v_mfma_f32_16x16x32_bf16 v[64:67], v[196:199], v[160:163], v[64:67]
	v_mfma_f32_16x16x32_bf16 v[68:71], v[204:207], v[160:163], v[68:71]
	v_mfma_f32_16x16x32_bf16 v[72:75], v[196:199], v[168:171], v[72:75]
	v_mfma_f32_16x16x32_bf16 v[76:79], v[204:207], v[168:171], v[76:79]
	v_mfma_f32_16x16x32_bf16 v[80:83], v[196:199], v[176:179], v[80:83]
	v_mfma_f32_16x16x32_bf16 v[84:87], v[204:207], v[176:179], v[84:87]
	v_mfma_f32_16x16x32_bf16 v[56:59], v[200:203], v[156:159], v[56:59]
	v_mfma_f32_16x16x32_bf16 v[60:63], v[208:211], v[156:159], v[60:63]
	v_mfma_f32_16x16x32_bf16 v[64:67], v[200:203], v[164:167], v[64:67]
	v_mfma_f32_16x16x32_bf16 v[68:71], v[208:211], v[164:167], v[68:71]
	v_mfma_f32_16x16x32_bf16 v[72:75], v[200:203], v[172:175], v[72:75]
	v_mfma_f32_16x16x32_bf16 v[76:79], v[208:211], v[172:175], v[76:79]
	v_mfma_f32_16x16x32_bf16 v[80:83], v[200:203], v[180:183], v[80:83]
	v_mfma_f32_16x16x32_bf16 v[84:87], v[208:211], v[180:183], v[84:87]
	s_setprio 0
	s_barrier
	ds_read_b128 v[152:155], v186 offset:16400
	ds_read_b128 v[156:159], v187 offset:16400
	ds_read_b128 v[160:163], v186 offset:18448
	ds_read_b128 v[164:167], v187 offset:18448
	ds_read_b128 v[168:171], v186 offset:20496
	ds_read_b128 v[172:175], v187 offset:20496
	ds_read_b128 v[176:179], v186 offset:22544
	ds_read_b128 v[180:183], v187 offset:22544
	s_cmp_lg_u32 s0, s54
	s_cbranch_scc1 .Lgu_nosw1
	s_mov_b64 s[66:67], s[74:75]
	s_mov_b64 s[70:71], s[80:81]
	s_mov_b64 s[72:73], s[82:83]

; #define LAS __attribute__((address_space(3)))
; #define BAR() { __builtin_amdgcn_sched_barrier(0); __builtin_amdgcn_s_barrier(); asm volatile("" ::: "memory"); __builtin_amdgcn_sched_barrier(0); }
; DI void gemm_stream2(const bf16_t* __restrict__ A, int lda, const bf16_t* __restrict__ Bt, int ldb, int K, int m0, int n0, ...
;     ...
; #pragma unroll
;         for (int ks = 0; ks < 2; ++ks) {
;             const unsigned fo = ks ? fo1 : fo0;
;             bf16x8 af[4], bfr[4];
; #pragma unroll
;             for (int i = 0; i < 4; ++i) { af[i] = *(const LAS bf16x8*)(base + aoff + i * 2048 + fo); bfr[i] = *(const LAS bf16x8*)(base + boff + i * 2048 + fo); }
;             if (ks == 1 && more) { if (pf) asm volatile("s_waitcnt vmcnt(3)" ::: "memory"); else asm volatile("s_waitcnt vmcnt(0)" ::: "memory"); }
;             if (pf) { PIECE(s2, ks * 3 + 0); PIECE(s2, ks * 3 + 1); PIECE(s2, ks * 3 + 2); }
;             asm volatile("s_waitcnt lgkmcnt(0)" ::: "memory");
;             BAR();
;             __builtin_amdgcn_s_setprio(1);
; #pragma unroll
;             for (int mi = 0; mi < 4; ++mi)
; #pragma unroll
;                 for (int ni = 0; ni < 4; ++ni) acc[mi][ni] = __builtin_amdgcn_mfma_f32_16x16x32_bf16(bfr[ni], af[mi], acc[mi][ni], 0, 0, 0);
;             __builtin_amdgcn_s_setprio(0);
;             BAR();
;         }
.Lgu_nosw2:
	s_add_i32 m0, s39, 0x4000
	s_nop 0
	global_load_lds_dwordx4 v184, s[68:69]
	s_add_i32 m0, s39, 0x4400
	s_nop 0
	global_load_lds_dwordx4 v185, s[68:69]
	s_add_u32 s68, s68, 0x80
	s_addc_u32 s69, s69, 0
	s_waitcnt lgkmcnt(0)
	s_waitcnt vmcnt(8)
	s_barrier
	s_setprio 1
	v_mfma_f32_16x16x32_bf16 v[24:27], v[0:3], v[152:155], v[24:27]
	v_mfma_f32_16x16x32_bf16 v[28:31], v[8:11], v[152:155], v[28:31]
	v_mfma_f32_16x16x32_bf16 v[32:35], v[0:3], v[160:163], v[32:35]
	v_mfma_f32_16x16x32_bf16 v[36:39], v[8:11], v[160:163], v[36:39]
	v_mfma_f32_16x16x32_bf16 v[40:43], v[0:3], v[168:171], v[40:43]
	v_mfma_f32_16x16x32_bf16 v[44:47], v[8:11], v[168:171], v[44:47]
	v_mfma_f32_16x16x32_bf16 v[48:51], v[0:3], v[176:179], v[48:51]
	v_mfma_f32_16x16x32_bf16 v[52:55], v[8:11], v[176:179], v[52:55]
	v_mfma_f32_16x16x32_bf16 v[24:27], v[4:7], v[156:159], v[24:27]
	v_mfma_f32_16x16x32_bf16 v[28:31], v[12:15], v[156:159], v[28:31]
	v_mfma_f32_16x16x32_bf16 v[32:35], v[4:7], v[164:167], v[32:35]
	v_mfma_f32_16x16x32_bf16 v[36:39], v[12:15], v[164:167], v[36:39]
	v_mfma_f32_16x16x32_bf16 v[40:43], v[4:7], v[172:175], v[40:43]
	v_mfma_f32_16x16x32_bf16 v[44:47], v[12:15], v[172:175], v[44:47]
	v_mfma_f32_16x16x32_bf16 v[48:51], v[4:7], v[180:183], v[48:51]
	v_mfma_f32_16x16x32_bf16 v[52:55], v[12:15], v[180:183], v[52:55]
	v_mfma_f32_16x16x32_bf16 v[56:59], v[196:199], v[152:155], v[56:59]
	v_mfma_f32_16x16x32_bf16 v[60:63], v[204:207], v[152:155], v[60:63]
	v_mfma_f32_16x16x32_bf16 v[64:67], v[196:199], v[160:163], v[64:67]
	v_mfma_f32_16x16x32_bf16 v[68:71], v[204:207], v[160:163], v[68:71]
	v_mfma_f32_16x16x32_bf16 v[72:75], v[196:199], v[168:171], v[72:75]
	v_mfma_f32_16x16x32_bf16 v[76:79], v[204:207], v[168:171], v[76:79]
	v_mfma_f32_16x16x32_bf16 v[80:83], v[196:199], v[176:179], v[80:83]
	v_mfma_f32_16x16x32_bf16 v[84:87], v[204:207], v[176:179], v[84:87]
	v_mfma_f32_16x16x32_bf16 v[56:59], v[200:203], v[156:159], v[56:59]
	v_mfma_f32_16x16x32_bf16 v[60:63], v[208:211], v[156:159], v[60:63]
	v_mfma_f32_16x16x32_bf16 v[64:67], v[200:203], v[164:167], v[64:67]
	v_mfma_f32_16x16x32_bf16 v[68:71], v[208:211], v[164:167], v[68:71]
	v_mfma_f32_16x16x32_bf16 v[72:75], v[200:203], v[172:175], v[72:75]
	v_mfma_f32_16x16x32_bf16 v[76:79], v[208:211], v[172:175], v[76:79]
	v_mfma_f32_16x16x32_bf16 v[80:83], v[200:203], v[180:183], v[80:83]
	v_mfma_f32_16x16x32_bf16 v[84:87], v[208:211], v[180:183], v[84:87]
	s_setprio 0
	s_barrier
	ds_read_b128 v[152:155], v186 offset:49168
	ds_read_b128 v[156:159], v187 offset:49168
	ds_read_b128 v[160:163], v186 offset:51216
	ds_read_b128 v[164:167], v187 offset:51216
	ds_read_b128 v[168:171], v186 offset:53264
	ds_read_b128 v[172:175], v187 offset:53264
	ds_read_b128 v[176:179], v186 offset:55312
	ds_read_b128 v[180:183], v187 offset:55312
	s_add_i32 m0, s39, 0x18000
	s_nop 0
	global_load_lds_dwordx4 v184, s[70:71]
	s_add_i32 m0, s39, 0x18400
	s_nop 0
	global_load_lds_dwordx4 v185, s[70:71]
	s_add_u32 s70, s70, 0x80
	s_addc_u32 s71, s71, 0
	s_add_i32 m0, s39, 0x8000
	s_nop 0
	global_load_lds_dwordx4 v184, s[66:67]
	s_add_i32 m0, s39, 0x8400
	s_nop 0
	global_load_lds_dwordx4 v185, s[66:67]
	s_add_u32 s66, s66, 0x80
	s_addc_u32 s67, s67, 0
	s_add_i32 m0, s39, 0x1c000
	s_nop 0
	global_load_lds_dwordx4 v184, s[72:73]
	s_add_i32 m0, s39, 0x1c400
	s_nop 0
	global_load_lds_dwordx4 v185, s[72:73]
	s_add_u32 s72, s72, 0x80
	s_addc_u32 s73, s73, 0
	s_waitcnt lgkmcnt(0)
	s_waitcnt vmcnt(8)
	s_nop 0
	s_barrier
	s_setprio 1
	v_mfma_f32_16x16x32_bf16 v[88:91], v[0:3], v[152:155], v[88:91]
	v_mfma_f32_16x16x32_bf16 v[92:95], v[8:11], v[152:155], v[92:95]
	v_mfma_f32_16x16x32_bf16 v[96:99], v[0:3], v[160:163], v[96:99]
	v_mfma_f32_16x16x32_bf16 v[100:103], v[8:11], v[160:163], v[100:103]
	v_mfma_f32_16x16x32_bf16 v[104:107], v[0:3], v[168:171], v[104:107]
	v_mfma_f32_16x16x32_bf16 v[108:111], v[8:11], v[168:171], v[108:111]
	v_mfma_f32_16x16x32_bf16 v[112:115], v[0:3], v[176:179], v[112:115]
	v_mfma_f32_16x16x32_bf16 v[116:119], v[8:11], v[176:179], v[116:119]
	v_mfma_f32_16x16x32_bf16 v[88:91], v[4:7], v[156:159], v[88:91]
	v_mfma_f32_16x16x32_bf16 v[92:95], v[12:15], v[156:159], v[92:95]
	v_mfma_f32_16x16x32_bf16 v[96:99], v[4:7], v[164:167], v[96:99]
	v_mfma_f32_16x16x32_bf16 v[100:103], v[12:15], v[164:167], v[100:103]
	v_mfma_f32_16x16x32_bf16 v[104:107], v[4:7], v[172:175], v[104:107]
	v_mfma_f32_16x16x32_bf16 v[108:111], v[12:15], v[172:175], v[108:111]
	v_mfma_f32_16x16x32_bf16 v[112:115], v[4:7], v[180:183], v[112:115]
	v_mfma_f32_16x16x32_bf16 v[116:119], v[12:15], v[180:183], v[116:119]
	v_mfma_f32_16x16x32_bf16 v[120:123], v[196:199], v[152:155], v[120:123]
	v_mfma_f32_16x16x32_bf16 v[124:127], v[204:207], v[152:155], v[124:127]
	v_mfma_f32_16x16x32_bf16 v[128:131], v[196:199], v[160:163], v[128:131]
	v_mfma_f32_16x16x32_bf16 v[132:135], v[204:207], v[160:163], v[132:135]
	v_mfma_f32_16x16x32_bf16 v[136:139], v[196:199], v[168:171], v[136:139]
	v_mfma_f32_16x16x32_bf16 v[140:143], v[204:207], v[168:171], v[140:143]
	v_mfma_f32_16x16x32_bf16 v[144:147], v[196:199], v[176:179], v[144:147]
	v_mfma_f32_16x16x32_bf16 v[148:151], v[204:207], v[176:179], v[148:151]
	v_mfma_f32_16x16x32_bf16 v[120:123], v[200:203], v[156:159], v[120:123]
	v_mfma_f32_16x16x32_bf16 v[124:127], v[208:211], v[156:159], v[124:127]
	v_mfma_f32_16x16x32_bf16 v[128:131], v[200:203], v[164:167], v[128:131]
	v_mfma_f32_16x16x32_bf16 v[132:135], v[208:211], v[164:167], v[132:135]
	v_mfma_f32_16x16x32_bf16 v[136:139], v[200:203], v[172:175], v[136:139]
	v_mfma_f32_16x16x32_bf16 v[140:143], v[208:211], v[172:175], v[140:143]
	v_mfma_f32_16x16x32_bf16 v[144:147], v[200:203], v[180:183], v[144:147]
	v_mfma_f32_16x16x32_bf16 v[148:151], v[208:211], v[180:183], v[148:151]
	s_setprio 0
	s_barrier
; #define LAS __attribute__((address_space(3)))
; #define BAR() { __builtin_amdgcn_sched_barrier(0); __builtin_amdgcn_s_barrier(); asm volatile("" ::: "memory"); __builtin_amdgcn_sched_barrier(0); }
; DI void gemm_stream2(const bf16_t* __restrict__ A, int lda, const bf16_t* __restrict__ Bt, int ldb, int K, int m0, int n0, ...
;     ...
;     for (int kt = 0; kt < nk; ++kt) {
;         const bool pf = (kt + 2 < nk) || has_next, more = (kt + 1 < nk) || has_next;
;         const bf16_t* pa = (kt + 2 < nk) ? ga + (kt + 2) * 64 : gan + (kt + 2 - nk) * 64;
;         const bf16_t* pb = (kt + 2 < nk) ? gb + (kt + 2) * 64 : gbn + (kt + 2 - nk) * 64;
;         const int plda = (kt + 2 < nk) ? lda : ldan, pldb = (kt + 2 < nk) ? ldb : ldbn;
;         const int s2 = st >= 1 ? st - 1 : 2;
;         const LAS char* base = lds + st * 49152;
; #pragma unroll
;         for (int ks = 0; ks < 2; ++ks) {
;             const unsigned fo = ks ? fo1 : fo0;
;             bf16x8 af[4], bfr[4];
; #pragma unroll
;             for (int i = 0; i < 4; ++i) { af[i] = *(const LAS bf16x8*)(base + aoff + i * 2048 + fo); bfr[i] = *(const LAS bf16x8*)(base + boff + i * 2048 + fo); }
;             if (ks == 1 && more) { if (pf) asm volatile("s_waitcnt vmcnt(3)" ::: "memory"); else asm volatile("s_waitcnt vmcnt(0)" ::: "memory"); }
;             if (pf) { PIECE(s2, ks * 3 + 0); PIECE(s2, ks * 3 + 1); PIECE(s2, ks * 3 + 2); }
;             asm volatile("s_waitcnt lgkmcnt(0)" ::: "memory");
;             BAR();
;             __builtin_amdgcn_s_setprio(1);
; #pragma unroll
;             for (int mi = 0; mi < 4; ++mi)
; #pragma unroll
;                 for (int ni = 0; ni < 4; ++ni) acc[mi][ni] = __builtin_amdgcn_mfma_f32_16x16x32_bf16(bfr[ni], af[mi], acc[mi][ni], 0, 0, 0);
;             __builtin_amdgcn_s_setprio(0);
;             BAR();
;         }
;         st = st == 2 ? 0 : st + 1;
;     }
;     if (grp == 0) BAR();
	s_sub_u32 s0, s0, 1
	s_cmp_lg_u32 s0, 0
	s_cbranch_scc1 .Lgu_kloop
	s_cmp_lg_u32 s54, 0
	s_cbranch_scc1 .Lgu_epi
	ds_read_b128 v[0:3], v188 offset:16
	ds_read_b128 v[4:7], v189 offset:16
	ds_read_b128 v[8:11], v188 offset:2064
	ds_read_b128 v[12:15], v189 offset:2064
	ds_read_b128 v[196:199], v188 offset:16400
	ds_read_b128 v[200:203], v189 offset:16400
	ds_read_b128 v[204:207], v188 offset:18448
	ds_read_b128 v[208:211], v189 offset:18448
	ds_read_b128 v[152:155], v186 offset:16
	ds_read_b128 v[156:159], v187 offset:16
	ds_read_b128 v[160:163], v186 offset:2064
	ds_read_b128 v[164:167], v187 offset:2064
	ds_read_b128 v[168:171], v186 offset:4112
	ds_read_b128 v[172:175], v187 offset:4112
	ds_read_b128 v[176:179], v186 offset:6160
	ds_read_b128 v[180:183], v187 offset:6160
	s_add_i32 m0, s39, 0xc000
	s_nop 0
	global_load_lds_dwordx4 v184, s[68:69]
	s_add_i32 m0, s39, 0xc400
	s_nop 0
	global_load_lds_dwordx4 v185, s[68:69]
	s_add_u32 s68, s68, 0x80
	s_addc_u32 s69, s69, 0
	s_waitcnt lgkmcnt(0)
	s_waitcnt vmcnt(8)
	s_barrier
	s_setprio 1
	v_mfma_f32_16x16x32_bf16 v[24:27], v[0:3], v[152:155], v[24:27]
	v_mfma_f32_16x16x32_bf16 v[28:31], v[8:11], v[152:155], v[28:31]
	v_mfma_f32_16x16x32_bf16 v[32:35], v[0:3], v[160:163], v[32:35]
	v_mfma_f32_16x16x32_bf16 v[36:39], v[8:11], v[160:163], v[36:39]
	v_mfma_f32_16x16x32_bf16 v[40:43], v[0:3], v[168:171], v[40:43]
	v_mfma_f32_16x16x32_bf16 v[44:47], v[8:11], v[168:171], v[44:47]
	v_mfma_f32_16x16x32_bf16 v[48:51], v[0:3], v[176:179], v[48:51]
	v_mfma_f32_16x16x32_bf16 v[52:55], v[8:11], v[176:179], v[52:55]
	v_mfma_f32_16x16x32_bf16 v[24:27], v[4:7], v[156:159], v[24:27]
	v_mfma_f32_16x16x32_bf16 v[28:31], v[12:15], v[156:159], v[28:31]
	v_mfma_f32_16x16x32_bf16 v[32:35], v[4:7], v[164:167], v[32:35]
	v_mfma_f32_16x16x32_bf16 v[36:39], v[12:15], v[164:167], v[36:39]
	v_mfma_f32_16x16x32_bf16 v[40:43], v[4:7], v[172:175], v[40:43]
	v_mfma_f32_16x16x32_bf16 v[44:47], v[12:15], v[172:175], v[44:47]
	v_mfma_f32_16x16x32_bf16 v[48:51], v[4:7], v[180:183], v[48:51]
	v_mfma_f32_16x16x32_bf16 v[52:55], v[12:15], v[180:183], v[52:55]
	v_mfma_f32_16x16x32_bf16 v[56:59], v[196:199], v[152:155], v[56:59]
	v_mfma_f32_16x16x32_bf16 v[60:63], v[204:207], v[152:155], v[60:63]
	v_mfma_f32_16x16x32_bf16 v[64:67], v[196:199], v[160:163], v[64:67]
	v_mfma_f32_16x16x32_bf16 v[68:71], v[204:207], v[160:163], v[68:71]
	v_mfma_f32_16x16x32_bf16 v[72:75], v[196:199], v[168:171], v[72:75]
	v_mfma_f32_16x16x32_bf16 v[76:79], v[204:207], v[168:171], v[76:79]
	v_mfma_f32_16x16x32_bf16 v[80:83], v[196:199], v[176:179], v[80:83]
	v_mfma_f32_16x16x32_bf16 v[84:87], v[204:207], v[176:179], v[84:87]
	v_mfma_f32_16x16x32_bf16 v[56:59], v[200:203], v[156:159], v[56:59]
	v_mfma_f32_16x16x32_bf16 v[60:63], v[208:211], v[156:159], v[60:63]
	v_mfma_f32_16x16x32_bf16 v[64:67], v[200:203], v[164:167], v[64:67]
	v_mfma_f32_16x16x32_bf16 v[68:71], v[208:211], v[164:167], v[68:71]
	v_mfma_f32_16x16x32_bf16 v[72:75], v[200:203], v[172:175], v[72:75]
	v_mfma_f32_16x16x32_bf16 v[76:79], v[208:211], v[172:175], v[76:79]
	v_mfma_f32_16x16x32_bf16 v[80:83], v[200:203], v[180:183], v[80:83]
	v_mfma_f32_16x16x32_bf16 v[84:87], v[208:211], v[180:183], v[84:87]
	s_setprio 0
	s_barrier
	ds_read_b128 v[152:155], v186 offset:16400
	ds_read_b128 v[156:159], v187 offset:16400
	ds_read_b128 v[160:163], v186 offset:18448
	ds_read_b128 v[164:167], v187 offset:18448
	ds_read_b128 v[168:171], v186 offset:20496
	ds_read_b128 v[172:175], v187 offset:20496
	ds_read_b128 v[176:179], v186 offset:22544
	ds_read_b128 v[180:183], v187 offset:22544
	s_waitcnt lgkmcnt(0)
	s_waitcnt vmcnt(2)
	s_barrier
	s_setprio 1
	v_mfma_f32_16x16x32_bf16 v[88:91], v[0:3], v[152:155], v[88:91]
	v_mfma_f32_16x16x32_bf16 v[92:95], v[8:11], v[152:155], v[92:95]
	v_mfma_f32_16x16x32_bf16 v[96:99], v[0:3], v[160:163], v[96:99]
	v_mfma_f32_16x16x32_bf16 v[100:103], v[8:11], v[160:163], v[100:103]
	v_mfma_f32_16x16x32_bf16 v[104:107], v[0:3], v[168:171], v[104:107]
	v_mfma_f32_16x16x32_bf16 v[108:111], v[8:11], v[168:171], v[108:111]
	v_mfma_f32_16x16x32_bf16 v[112:115], v[0:3], v[176:179], v[112:115]
	v_mfma_f32_16x16x32_bf16 v[116:119], v[8:11], v[176:179], v[116:119]
	v_mfma_f32_16x16x32_bf16 v[88:91], v[4:7], v[156:159], v[88:91]
	v_mfma_f32_16x16x32_bf16 v[92:95], v[12:15], v[156:159], v[92:95]
	v_mfma_f32_16x16x32_bf16 v[96:99], v[4:7], v[164:167], v[96:99]
	v_mfma_f32_16x16x32_bf16 v[100:103], v[12:15], v[164:167], v[100:103]
	v_mfma_f32_16x16x32_bf16 v[104:107], v[4:7], v[172:175], v[104:107]
	v_mfma_f32_16x16x32_bf16 v[108:111], v[12:15], v[172:175], v[108:111]
	v_mfma_f32_16x16x32_bf16 v[112:115], v[4:7], v[180:183], v[112:115]
	v_mfma_f32_16x16x32_bf16 v[116:119], v[12:15], v[180:183], v[116:119]
	v_mfma_f32_16x16x32_bf16 v[120:123], v[196:199], v[152:155], v[120:123]
	v_mfma_f32_16x16x32_bf16 v[124:127], v[204:207], v[152:155], v[124:127]
	v_mfma_f32_16x16x32_bf16 v[128:131], v[196:199], v[160:163], v[128:131]
	v_mfma_f32_16x16x32_bf16 v[132:135], v[204:207], v[160:163], v[132:135]
	v_mfma_f32_16x16x32_bf16 v[136:139], v[196:199], v[168:171], v[136:139]
	v_mfma_f32_16x16x32_bf16 v[140:143], v[204:207], v[168:171], v[140:143]
	v_mfma_f32_16x16x32_bf16 v[144:147], v[196:199], v[176:179], v[144:147]
	v_mfma_f32_16x16x32_bf16 v[148:151], v[204:207], v[176:179], v[148:151]
	v_mfma_f32_16x16x32_bf16 v[120:123], v[200:203], v[156:159], v[120:123]
	v_mfma_f32_16x16x32_bf16 v[124:127], v[208:211], v[156:159], v[124:127]
	v_mfma_f32_16x16x32_bf16 v[128:131], v[200:203], v[164:167], v[128:131]
	v_mfma_f32_16x16x32_bf16 v[132:135], v[208:211], v[164:167], v[132:135]
	v_mfma_f32_16x16x32_bf16 v[136:139], v[200:203], v[172:175], v[136:139]
	v_mfma_f32_16x16x32_bf16 v[140:143], v[208:211], v[172:175], v[140:143]
	v_mfma_f32_16x16x32_bf16 v[144:147], v[200:203], v[180:183], v[144:147]
	v_mfma_f32_16x16x32_bf16 v[148:151], v[208:211], v[180:183], v[148:151]
	s_setprio 0
	s_barrier
; #define LAS __attribute__((address_space(3)))
; #define BAR() { __builtin_amdgcn_sched_barrier(0); __builtin_amdgcn_s_barrier(); asm volatile("" ::: "memory"); __builtin_amdgcn_sched_barrier(0); }
; DI void gemm_stream2(const bf16_t* __restrict__ A, int lda, const bf16_t* __restrict__ Bt, int ldb, int K, int m0, int n0, ...
;     ...
; #pragma unroll
;         for (int ks = 0; ks < 2; ++ks) {
;             const unsigned fo = ks ? fo1 : fo0;
;             bf16x8 af[4], bfr[4];
; #pragma unroll
;             for (int i = 0; i < 4; ++i) { af[i] = *(const LAS bf16x8*)(base + aoff + i * 2048 + fo); bfr[i] = *(const LAS bf16x8*)(base + boff + i * 2048 + fo); }
;             if (ks == 1 && more) { if (pf) asm volatile("s_waitcnt vmcnt(3)" ::: "memory"); else asm volatile("s_waitcnt vmcnt(0)" ::: "memory"); }
;             if (pf) { PIECE(s2, ks * 3 + 0); PIECE(s2, ks * 3 + 1); PIECE(s2, ks * 3 + 2); }
;             asm volatile("s_waitcnt lgkmcnt(0)" ::: "memory");
;             BAR();
;             __builtin_amdgcn_s_setprio(1);
; #pragma unroll
;             for (int mi = 0; mi < 4; ++mi)
; #pragma unroll
;                 for (int ni = 0; ni < 4; ++ni) acc[mi][ni] = __builtin_amdgcn_mfma_f32_16x16x32_bf16(bfr[ni], af[mi], acc[mi][ni], 0, 0, 0);
;             __builtin_amdgcn_s_setprio(0);
;             BAR();
;         }
;         st = st == 2 ? 0 : st + 1;
;     }
;     if (grp == 0) BAR();
	ds_read_b128 v[0:3], v188 offset:32784
	ds_read_b128 v[4:7], v189 offset:32784
	ds_read_b128 v[8:11], v188 offset:34832
	ds_read_b128 v[12:15], v189 offset:34832
	ds_read_b128 v[196:199], v188 offset:49168
	ds_read_b128 v[200:203], v189 offset:49168
	ds_read_b128 v[204:207], v188 offset:51216
	ds_read_b128 v[208:211], v189 offset:51216
	ds_read_b128 v[152:155], v186 offset:32784
	ds_read_b128 v[156:159], v187 offset:32784
	ds_read_b128 v[160:163], v186 offset:34832
	ds_read_b128 v[164:167], v187 offset:34832
	ds_read_b128 v[168:171], v186 offset:36880
	ds_read_b128 v[172:175], v187 offset:36880
	ds_read_b128 v[176:179], v186 offset:38928
	ds_read_b128 v[180:183], v187 offset:38928
	s_waitcnt lgkmcnt(0)
	s_waitcnt vmcnt(0)
	s_barrier
	s_setprio 1
	v_mfma_f32_16x16x32_bf16 v[24:27], v[0:3], v[152:155], v[24:27]
	v_mfma_f32_16x16x32_bf16 v[28:31], v[8:11], v[152:155], v[28:31]
	v_mfma_f32_16x16x32_bf16 v[32:35], v[0:3], v[160:163], v[32:35]
	v_mfma_f32_16x16x32_bf16 v[36:39], v[8:11], v[160:163], v[36:39]
	v_mfma_f32_16x16x32_bf16 v[40:43], v[0:3], v[168:171], v[40:43]
	v_mfma_f32_16x16x32_bf16 v[44:47], v[8:11], v[168:171], v[44:47]
	v_mfma_f32_16x16x32_bf16 v[48:51], v[0:3], v[176:179], v[48:51]
	v_mfma_f32_16x16x32_bf16 v[52:55], v[8:11], v[176:179], v[52:55]
	v_mfma_f32_16x16x32_bf16 v[24:27], v[4:7], v[156:159], v[24:27]
	v_mfma_f32_16x16x32_bf16 v[28:31], v[12:15], v[156:159], v[28:31]
	v_mfma_f32_16x16x32_bf16 v[32:35], v[4:7], v[164:167], v[32:35]
	v_mfma_f32_16x16x32_bf16 v[36:39], v[12:15], v[164:167], v[36:39]
	v_mfma_f32_16x16x32_bf16 v[40:43], v[4:7], v[172:175], v[40:43]
	v_mfma_f32_16x16x32_bf16 v[44:47], v[12:15], v[172:175], v[44:47]
	v_mfma_f32_16x16x32_bf16 v[48:51], v[4:7], v[180:183], v[48:51]
	v_mfma_f32_16x16x32_bf16 v[52:55], v[12:15], v[180:183], v[52:55]
	v_mfma_f32_16x16x32_bf16 v[56:59], v[196:199], v[152:155], v[56:59]
	v_mfma_f32_16x16x32_bf16 v[60:63], v[204:207], v[152:155], v[60:63]
	v_mfma_f32_16x16x32_bf16 v[64:67], v[196:199], v[160:163], v[64:67]
	v_mfma_f32_16x16x32_bf16 v[68:71], v[204:207], v[160:163], v[68:71]
	v_mfma_f32_16x16x32_bf16 v[72:75], v[196:199], v[168:171], v[72:75]
	v_mfma_f32_16x16x32_bf16 v[76:79], v[204:207], v[168:171], v[76:79]
	v_mfma_f32_16x16x32_bf16 v[80:83], v[196:199], v[176:179], v[80:83]
	v_mfma_f32_16x16x32_bf16 v[84:87], v[204:207], v[176:179], v[84:87]
	v_mfma_f32_16x16x32_bf16 v[56:59], v[200:203], v[156:159], v[56:59]
	v_mfma_f32_16x16x32_bf16 v[60:63], v[208:211], v[156:159], v[60:63]
	v_mfma_f32_16x16x32_bf16 v[64:67], v[200:203], v[164:167], v[64:67]
	v_mfma_f32_16x16x32_bf16 v[68:71], v[208:211], v[164:167], v[68:71]
	v_mfma_f32_16x16x32_bf16 v[72:75], v[200:203], v[172:175], v[72:75]
	v_mfma_f32_16x16x32_bf16 v[76:79], v[208:211], v[172:175], v[76:79]
	v_mfma_f32_16x16x32_bf16 v[80:83], v[200:203], v[180:183], v[80:83]
	v_mfma_f32_16x16x32_bf16 v[84:87], v[208:211], v[180:183], v[84:87]
	s_setprio 0
	s_barrier
	ds_read_b128 v[152:155], v186 offset:49168
	ds_read_b128 v[156:159], v187 offset:49168
	ds_read_b128 v[160:163], v186 offset:51216
	ds_read_b128 v[164:167], v187 offset:51216
	ds_read_b128 v[168:171], v186 offset:53264
	ds_read_b128 v[172:175], v187 offset:53264
	ds_read_b128 v[176:179], v186 offset:55312
	ds_read_b128 v[180:183], v187 offset:55312
	s_waitcnt lgkmcnt(0)
	s_barrier
	s_setprio 1
	v_mfma_f32_16x16x32_bf16 v[88:91], v[0:3], v[152:155], v[88:91]
	v_mfma_f32_16x16x32_bf16 v[92:95], v[8:11], v[152:155], v[92:95]
	v_mfma_f32_16x16x32_bf16 v[96:99], v[0:3], v[160:163], v[96:99]
	v_mfma_f32_16x16x32_bf16 v[100:103], v[8:11], v[160:163], v[100:103]
	v_mfma_f32_16x16x32_bf16 v[104:107], v[0:3], v[168:171], v[104:107]
	v_mfma_f32_16x16x32_bf16 v[108:111], v[8:11], v[168:171], v[108:111]
	v_mfma_f32_16x16x32_bf16 v[112:115], v[0:3], v[176:179], v[112:115]
	v_mfma_f32_16x16x32_bf16 v[116:119], v[8:11], v[176:179], v[116:119]
	v_mfma_f32_16x16x32_bf16 v[88:91], v[4:7], v[156:159], v[88:91]
	v_mfma_f32_16x16x32_bf16 v[92:95], v[12:15], v[156:159], v[92:95]
	v_mfma_f32_16x16x32_bf16 v[96:99], v[4:7], v[164:167], v[96:99]
	v_mfma_f32_16x16x32_bf16 v[100:103], v[12:15], v[164:167], v[100:103]
	v_mfma_f32_16x16x32_bf16 v[104:107], v[4:7], v[172:175], v[104:107]
	v_mfma_f32_16x16x32_bf16 v[108:111], v[12:15], v[172:175], v[108:111]
	v_mfma_f32_16x16x32_bf16 v[112:115], v[4:7], v[180:183], v[112:115]
	v_mfma_f32_16x16x32_bf16 v[116:119], v[12:15], v[180:183], v[116:119]
	v_mfma_f32_16x16x32_bf16 v[120:123], v[196:199], v[152:155], v[120:123]
	v_mfma_f32_16x16x32_bf16 v[124:127], v[204:207], v[152:155], v[124:127]
	v_mfma_f32_16x16x32_bf16 v[128:131], v[196:199], v[160:163], v[128:131]
	v_mfma_f32_16x16x32_bf16 v[132:135], v[204:207], v[160:163], v[132:135]
	v_mfma_f32_16x16x32_bf16 v[136:139], v[196:199], v[168:171], v[136:139]
	v_mfma_f32_16x16x32_bf16 v[140:143], v[204:207], v[168:171], v[140:143]
	v_mfma_f32_16x16x32_bf16 v[144:147], v[196:199], v[176:179], v[144:147]
	v_mfma_f32_16x16x32_bf16 v[148:151], v[204:207], v[176:179], v[148:151]
	v_mfma_f32_16x16x32_bf16 v[120:123], v[200:203], v[156:159], v[120:123]
	v_mfma_f32_16x16x32_bf16 v[124:127], v[208:211], v[156:159], v[124:127]
	v_mfma_f32_16x16x32_bf16 v[128:131], v[200:203], v[164:167], v[128:131]
	v_mfma_f32_16x16x32_bf16 v[132:135], v[208:211], v[164:167], v[132:135]
	v_mfma_f32_16x16x32_bf16 v[136:139], v[200:203], v[172:175], v[136:139]
	v_mfma_f32_16x16x32_bf16 v[140:143], v[208:211], v[172:175], v[140:143]
	v_mfma_f32_16x16x32_bf16 v[144:147], v[200:203], v[180:183], v[144:147]
	v_mfma_f32_16x16x32_bf16 v[148:151], v[208:211], v[180:183], v[148:151]
	s_setprio 0
	s_barrier
	s_cmp_lg_u32 s33, 0
	s_cbranch_scc1 .Lgu_epi
	s_barrier

; #define LAS __attribute__((address_space(3)))
; #define BAR() { __builtin_amdgcn_sched_barrier(0); __builtin_amdgcn_s_barrier(); asm volatile("" ::: "memory"); __builtin_amdgcn_sched_barrier(0); }
; DI void gemm_stream2(const bf16_t* __restrict__ A, int lda, const bf16_t* __restrict__ Bt, int ldb, int K, int m0, int n0, ...
;     ...
; #pragma unroll
;         for (int ks = 0; ks < 2; ++ks) {
;             const unsigned fo = ks ? fo1 : fo0;
;             bf16x8 af[4], bfr[4];
; #pragma unroll
;             for (int i = 0; i < 4; ++i) { af[i] = *(const LAS bf16x8*)(base + aoff + i * 2048 + fo); bfr[i] = *(const LAS bf16x8*)(base + boff + i * 2048 + fo); }
;             if (ks == 1 && more) { if (pf) asm volatile("s_waitcnt vmcnt(3)" ::: "memory"); else asm volatile("s_waitcnt vmcnt(0)" ::: "memory"); }
;             if (pf) { PIECE(s2, ks * 3 + 0); PIECE(s2, ks * 3 + 1); PIECE(s2, ks * 3 + 2); }
;             asm volatile("s_waitcnt lgkmcnt(0)" ::: "memory");
;             BAR();
;             __builtin_amdgcn_s_setprio(1);
; #pragma unroll
;             for (int mi = 0; mi < 4; ++mi)
; #pragma unroll
;                 for (int ni = 0; ni < 4; ++ni) acc[mi][ni] = __builtin_amdgcn_mfma_f32_16x16x32_bf16(bfr[ni], af[mi], acc[mi][ni], 0, 0, 0);
;             __builtin_amdgcn_s_setprio(0);
;             BAR();
;         }
.Lgyd_nosw2:
	s_add_i32 m0, s39, 0x4000
	s_nop 0
	global_load_lds_dwordx4 v184, s[68:69]
	s_add_i32 m0, s39, 0x4400
	s_nop 0
	global_load_lds_dwordx4 v185, s[68:69]
	s_add_u32 s68, s68, 0x80
	s_addc_u32 s69, s69, 0
	s_waitcnt lgkmcnt(0)
	s_waitcnt vmcnt(8)
	s_barrier
	s_setprio 1
	v_mfma_f32_16x16x32_bf16 v[24:27], v[0:3], v[152:155], v[24:27]
	v_mfma_f32_16x16x32_bf16 v[28:31], v[8:11], v[152:155], v[28:31]
	v_mfma_f32_16x16x32_bf16 v[32:35], v[0:3], v[160:163], v[32:35]
	v_mfma_f32_16x16x32_bf16 v[36:39], v[8:11], v[160:163], v[36:39]
	v_mfma_f32_16x16x32_bf16 v[40:43], v[0:3], v[168:171], v[40:43]
	v_mfma_f32_16x16x32_bf16 v[44:47], v[8:11], v[168:171], v[44:47]
	v_mfma_f32_16x16x32_bf16 v[48:51], v[0:3], v[176:179], v[48:51]
	v_mfma_f32_16x16x32_bf16 v[52:55], v[8:11], v[176:179], v[52:55]
	v_mfma_f32_16x16x32_bf16 v[24:27], v[4:7], v[156:159], v[24:27]
	v_mfma_f32_16x16x32_bf16 v[28:31], v[12:15], v[156:159], v[28:31]
	v_mfma_f32_16x16x32_bf16 v[32:35], v[4:7], v[164:167], v[32:35]
	v_mfma_f32_16x16x32_bf16 v[36:39], v[12:15], v[164:167], v[36:39]
	v_mfma_f32_16x16x32_bf16 v[40:43], v[4:7], v[172:175], v[40:43]
	v_mfma_f32_16x16x32_bf16 v[44:47], v[12:15], v[172:175], v[44:47]
	v_mfma_f32_16x16x32_bf16 v[48:51], v[4:7], v[180:183], v[48:51]
	v_mfma_f32_16x16x32_bf16 v[52:55], v[12:15], v[180:183], v[52:55]
	v_mfma_f32_16x16x32_bf16 v[56:59], v[196:199], v[152:155], v[56:59]
	v_mfma_f32_16x16x32_bf16 v[60:63], v[204:207], v[152:155], v[60:63]
	v_mfma_f32_16x16x32_bf16 v[64:67], v[196:199], v[160:163], v[64:67]
	v_mfma_f32_16x16x32_bf16 v[68:71], v[204:207], v[160:163], v[68:71]
	v_mfma_f32_16x16x32_bf16 v[72:75], v[196:199], v[168:171], v[72:75]
	v_mfma_f32_16x16x32_bf16 v[76:79], v[204:207], v[168:171], v[76:79]
	v_mfma_f32_16x16x32_bf16 v[80:83], v[196:199], v[176:179], v[80:83]
	v_mfma_f32_16x16x32_bf16 v[84:87], v[204:207], v[176:179], v[84:87]
	v_mfma_f32_16x16x32_bf16 v[56:59], v[200:203], v[156:159], v[56:59]
	v_mfma_f32_16x16x32_bf16 v[60:63], v[208:211], v[156:159], v[60:63]
	v_mfma_f32_16x16x32_bf16 v[64:67], v[200:203], v[164:167], v[64:67]
	v_mfma_f32_16x16x32_bf16 v[68:71], v[208:211], v[164:167], v[68:71]
	v_mfma_f32_16x16x32_bf16 v[72:75], v[200:203], v[172:175], v[72:75]
	v_mfma_f32_16x16x32_bf16 v[76:79], v[208:211], v[172:175], v[76:79]
	v_mfma_f32_16x16x32_bf16 v[80:83], v[200:203], v[180:183], v[80:83]
	v_mfma_f32_16x16x32_bf16 v[84:87], v[208:211], v[180:183], v[84:87]
	s_setprio 0
	s_barrier
	ds_read_b128 v[152:155], v186 offset:49168
	ds_read_b128 v[156:159], v187 offset:49168
	ds_read_b128 v[160:163], v186 offset:51216
	ds_read_b128 v[164:167], v187 offset:51216
	ds_read_b128 v[168:171], v186 offset:53264
	ds_read_b128 v[172:175], v187 offset:53264
	ds_read_b128 v[176:179], v186 offset:55312
	ds_read_b128 v[180:183], v187 offset:55312
	s_add_i32 m0, s39, 0x18000
	s_nop 0
	global_load_lds_dwordx4 v184, s[70:71]
	s_add_i32 m0, s39, 0x18400
	s_nop 0
	global_load_lds_dwordx4 v185, s[70:71]
	s_add_u32 s70, s70, 0x80
	s_addc_u32 s71, s71, 0
	s_add_i32 m0, s39, 0x8000
	s_nop 0
	global_load_lds_dwordx4 v184, s[66:67]
	s_add_i32 m0, s39, 0x8400
	s_nop 0
	global_load_lds_dwordx4 v185, s[66:67]
	s_add_u32 s66, s66, 0x80
	s_addc_u32 s67, s67, 0
	s_add_i32 m0, s39, 0x1c000
	s_nop 0
	global_load_lds_dwordx4 v184, s[72:73]
	s_add_i32 m0, s39, 0x1c400
	s_nop 0
	global_load_lds_dwordx4 v185, s[72:73]
	s_add_u32 s72, s72, 0x80
	s_addc_u32 s73, s73, 0
	s_waitcnt lgkmcnt(0)
	s_waitcnt vmcnt(8)
	s_nop 0
	s_barrier
	s_setprio 1
	v_mfma_f32_16x16x32_bf16 v[88:91], v[0:3], v[152:155], v[88:91]
	v_mfma_f32_16x16x32_bf16 v[92:95], v[8:11], v[152:155], v[92:95]
	v_mfma_f32_16x16x32_bf16 v[96:99], v[0:3], v[160:163], v[96:99]
	v_mfma_f32_16x16x32_bf16 v[100:103], v[8:11], v[160:163], v[100:103]
	v_mfma_f32_16x16x32_bf16 v[104:107], v[0:3], v[168:171], v[104:107]
	v_mfma_f32_16x16x32_bf16 v[108:111], v[8:11], v[168:171], v[108:111]
	v_mfma_f32_16x16x32_bf16 v[112:115], v[0:3], v[176:179], v[112:115]
	v_mfma_f32_16x16x32_bf16 v[116:119], v[8:11], v[176:179], v[116:119]
	v_mfma_f32_16x16x32_bf16 v[88:91], v[4:7], v[156:159], v[88:91]
	v_mfma_f32_16x16x32_bf16 v[92:95], v[12:15], v[156:159], v[92:95]
	v_mfma_f32_16x16x32_bf16 v[96:99], v[4:7], v[164:167], v[96:99]
	v_mfma_f32_16x16x32_bf16 v[100:103], v[12:15], v[164:167], v[100:103]
	v_mfma_f32_16x16x32_bf16 v[104:107], v[4:7], v[172:175], v[104:107]
	v_mfma_f32_16x16x32_bf16 v[108:111], v[12:15], v[172:175], v[108:111]
	v_mfma_f32_16x16x32_bf16 v[112:115], v[4:7], v[180:183], v[112:115]
	v_mfma_f32_16x16x32_bf16 v[116:119], v[12:15], v[180:183], v[116:119]
	v_mfma_f32_16x16x32_bf16 v[120:123], v[196:199], v[152:155], v[120:123]
	v_mfma_f32_16x16x32_bf16 v[124:127], v[204:207], v[152:155], v[124:127]
	v_mfma_f32_16x16x32_bf16 v[128:131], v[196:199], v[160:163], v[128:131]
	v_mfma_f32_16x16x32_bf16 v[132:135], v[204:207], v[160:163], v[132:135]
	v_mfma_f32_16x16x32_bf16 v[136:139], v[196:199], v[168:171], v[136:139]
	v_mfma_f32_16x16x32_bf16 v[140:143], v[204:207], v[168:171], v[140:143]
	v_mfma_f32_16x16x32_bf16 v[144:147], v[196:199], v[176:179], v[144:147]
	v_mfma_f32_16x16x32_bf16 v[148:151], v[204:207], v[176:179], v[148:151]
	v_mfma_f32_16x16x32_bf16 v[120:123], v[200:203], v[156:159], v[120:123]
	v_mfma_f32_16x16x32_bf16 v[124:127], v[208:211], v[156:159], v[124:127]
	v_mfma_f32_16x16x32_bf16 v[128:131], v[200:203], v[164:167], v[128:131]
	v_mfma_f32_16x16x32_bf16 v[132:135], v[208:211], v[164:167], v[132:135]
	v_mfma_f32_16x16x32_bf16 v[136:139], v[200:203], v[172:175], v[136:139]
	v_mfma_f32_16x16x32_bf16 v[140:143], v[208:211], v[172:175], v[140:143]
	v_mfma_f32_16x16x32_bf16 v[144:147], v[200:203], v[180:183], v[144:147]
	v_mfma_f32_16x16x32_bf16 v[148:151], v[208:211], v[180:183], v[148:151]
	s_setprio 0
	s_barrier
	s_sub_u32 s0, s0, 1
	s_cmp_lg_u32 s0, 0
	s_cbranch_scc1 .Lgyd_kloop
